# v26 variant: recurrence LDS reads spread through the step with counted partial lgkmcnt waits before each consumer group
# baseline (speedup 1.0000x reference)
.LBB0_1238:
	s_or_b64 exec, exec, s[18:19]
	s_waitcnt lgkmcnt(0)
	s_barrier
	s_cmp_lg_u32 s100, 0
	s_cselect_b32 s97, 0x800, 0
	v_add_u32_e32 v167, s97, v114
	ds_read_b128 v[72:75], v114 offset:41216
	ds_read_b128 v[68:71], v114 offset:45312
	ds_read_b128 v[64:67], v114 offset:49408
	ds_read2st64_b32 v[214:215], v115 offset0:0 offset1:1
	ds_read_b128 v[60:63], v167 offset:28928
	ds_read_b128 v[56:59], v114 offset:53504
	s_waitcnt lgkmcnt(5)
	v_dot2_f32_f16 v151, v127, v72, 0
	v_dot2_f32_f16 v151, v126, v73, v151
	v_dot2_f32_f16 v151, v125, v74, v151
	v_dot2_f32_f16 v151, v124, v75, v151
	ds_read_b128 v[134:137], v114 offset:41344
	ds_read_b128 v[138:141], v114 offset:45440
	ds_read_b128 v[142:145], v114 offset:49536
	v_add_f32_dpp v151, v151, v151 quad_perm:[1,0,3,2] row_mask:0xf bank_mask:0xf bound_ctrl:1
	ds_read_b128 v[130:133], v167 offset:29056
	ds_read_b128 v[146:149], v114 offset:53632
	v_add_f32_dpp v151, v151, v151 quad_perm:[2,3,0,1] row_mask:0xf bank_mask:0xf bound_ctrl:1
	s_nop 1
	v_add_f32_dpp v151, v151, v151 row_half_mirror row_mask:0xf bank_mask:0xf bound_ctrl:1
	v_cvt_pkrtz_f16_f32 v152, -v151, -v151
	s_waitcnt lgkmcnt(9)
	v_pk_mul_f16 v153, v152, v68
	v_pk_mul_f16 v154, v152, v69
	v_pk_mul_f16 v155, v152, v70
	v_pk_mul_f16 v156, v152, v71
	s_waitcnt lgkmcnt(7)
	v_pk_fma_f16 v153, v214, v64, v153
	v_pk_fma_f16 v154, v214, v65, v154
	v_pk_fma_f16 v155, v214, v66, v155
	v_pk_fma_f16 v156, v214, v67, v156
	s_waitcnt lgkmcnt(6)
	v_pk_fma_f16 v127, v127, v60, v153
	v_pk_fma_f16 v126, v126, v61, v154
	v_pk_fma_f16 v125, v125, v62, v155
	v_pk_fma_f16 v124, v124, v63, v156
	s_waitcnt lgkmcnt(4)
	v_dot2_f32_f16 v151, v127, v134, 0
	v_dot2_f32_f16 v151, v126, v135, v151
	v_dot2_f32_f16 v151, v125, v136, v151
	v_dot2_f32_f16 v151, v124, v137, v151
	v_dot2_f32_f16 v157, v127, v56, 0
	v_dot2_f32_f16 v157, v126, v57, v157
	v_dot2_f32_f16 v157, v125, v58, v157
	v_add_f32_dpp v151, v151, v151 quad_perm:[1,0,3,2] row_mask:0xf bank_mask:0xf bound_ctrl:1
	v_dot2_f32_f16 v157, v124, v59, v157
	ds_read_b128 v[72:75], v114 offset:41472
	v_add_f32_dpp v151, v151, v151 quad_perm:[2,3,0,1] row_mask:0xf bank_mask:0xf bound_ctrl:1
	ds_read_b128 v[68:71], v114 offset:45568
	ds_read_b128 v[64:67], v114 offset:49664
	v_add_f32_dpp v151, v151, v151 row_half_mirror row_mask:0xf bank_mask:0xf bound_ctrl:1
	v_cvt_pkrtz_f16_f32 v152, -v151, -v151
	s_waitcnt lgkmcnt(6)
	v_pk_mul_f16 v153, v152, v138
	v_pk_mul_f16 v154, v152, v139
	ds_read2st64_b32 v[216:217], v115 offset0:2 offset1:3
	v_pk_mul_f16 v155, v152, v140
	v_pk_mul_f16 v156, v152, v141
	s_waitcnt lgkmcnt(6)
	v_pk_fma_f16 v153, v215, v142, v153
	v_pk_fma_f16 v154, v215, v143, v154
	ds_read_b128 v[60:63], v167 offset:29184
	v_pk_fma_f16 v155, v215, v144, v155
	v_pk_fma_f16 v156, v215, v145, v156
	s_waitcnt lgkmcnt(6)
	v_pk_fma_f16 v127, v127, v130, v153
	v_pk_fma_f16 v126, v126, v131, v154
	ds_read_b128 v[56:59], v114 offset:53760
	v_pk_fma_f16 v125, v125, v132, v155
	v_pk_fma_f16 v124, v124, v133, v156
	s_waitcnt lgkmcnt(5)
	v_dot2_f32_f16 v151, v127, v72, 0
	v_dot2_f32_f16 v151, v126, v73, v151
	v_dot2_f32_f16 v151, v125, v74, v151
	v_dot2_f32_f16 v151, v124, v75, v151
	v_dot2_f32_f16 v158, v127, v146, 0
	v_dot2_f32_f16 v158, v126, v147, v158
	v_dot2_f32_f16 v158, v125, v148, v158
	v_add_f32_dpp v151, v151, v151 quad_perm:[1,0,3,2] row_mask:0xf bank_mask:0xf bound_ctrl:1
	v_dot2_f32_f16 v158, v124, v149, v158
	ds_read_b128 v[134:137], v114 offset:41600
	v_add_f32_dpp v151, v151, v151 quad_perm:[2,3,0,1] row_mask:0xf bank_mask:0xf bound_ctrl:1
	ds_read_b128 v[138:141], v114 offset:45696
	ds_read_b128 v[142:145], v114 offset:49792
	v_add_f32_dpp v151, v151, v151 row_half_mirror row_mask:0xf bank_mask:0xf bound_ctrl:1
	v_cvt_pkrtz_f16_f32 v152, -v151, -v151
	s_waitcnt lgkmcnt(7)
	v_pk_mul_f16 v153, v152, v68
	v_pk_mul_f16 v154, v152, v69
	ds_read_b128 v[130:133], v167 offset:29312
	v_pk_mul_f16 v155, v152, v70
	v_pk_mul_f16 v156, v152, v71
	s_waitcnt lgkmcnt(6)
	v_pk_fma_f16 v153, v216, v64, v153
	v_pk_fma_f16 v154, v216, v65, v154
	ds_read_b128 v[146:149], v114 offset:53888
	v_pk_fma_f16 v155, v216, v66, v155
	v_pk_fma_f16 v156, v216, v67, v156
	s_waitcnt lgkmcnt(6)
	v_pk_fma_f16 v127, v127, v60, v153
	v_pk_fma_f16 v126, v126, v61, v154
	ds_write2st64_b32 v116, v157, v158 offset0:0 offset1:8
	v_pk_fma_f16 v125, v125, v62, v155
	v_pk_fma_f16 v124, v124, v63, v156
	s_waitcnt lgkmcnt(5)
	v_dot2_f32_f16 v151, v127, v134, 0
	v_dot2_f32_f16 v151, v126, v135, v151
	v_dot2_f32_f16 v151, v125, v136, v151
	v_dot2_f32_f16 v151, v124, v137, v151
	v_dot2_f32_f16 v157, v127, v56, 0
	v_dot2_f32_f16 v157, v126, v57, v157
	v_dot2_f32_f16 v157, v125, v58, v157
	v_add_f32_dpp v151, v151, v151 quad_perm:[1,0,3,2] row_mask:0xf bank_mask:0xf bound_ctrl:1
	v_dot2_f32_f16 v157, v124, v59, v157
	ds_read_b128 v[72:75], v114 offset:41728
	v_add_f32_dpp v151, v151, v151 quad_perm:[2,3,0,1] row_mask:0xf bank_mask:0xf bound_ctrl:1
	ds_read_b128 v[68:71], v114 offset:45824
	ds_read_b128 v[64:67], v114 offset:49920
	v_add_f32_dpp v151, v151, v151 row_half_mirror row_mask:0xf bank_mask:0xf bound_ctrl:1
	v_cvt_pkrtz_f16_f32 v152, -v151, -v151
	s_waitcnt lgkmcnt(7)
	v_pk_mul_f16 v153, v152, v138
	v_pk_mul_f16 v154, v152, v139
	ds_read2st64_b32 v[214:215], v115 offset0:4 offset1:5
	v_pk_mul_f16 v155, v152, v140
	v_pk_mul_f16 v156, v152, v141
	s_waitcnt lgkmcnt(7)
	v_pk_fma_f16 v153, v217, v142, v153
	v_pk_fma_f16 v154, v217, v143, v154
	ds_read_b128 v[60:63], v167 offset:29440
	v_pk_fma_f16 v155, v217, v144, v155
	v_pk_fma_f16 v156, v217, v145, v156
	s_waitcnt lgkmcnt(7)
	v_pk_fma_f16 v127, v127, v130, v153
	v_pk_fma_f16 v126, v126, v131, v154
	ds_read_b128 v[56:59], v114 offset:54016
	v_pk_fma_f16 v125, v125, v132, v155
	v_pk_fma_f16 v124, v124, v133, v156
	s_waitcnt lgkmcnt(5)
	v_dot2_f32_f16 v151, v127, v72, 0
	v_dot2_f32_f16 v151, v126, v73, v151
	v_dot2_f32_f16 v151, v125, v74, v151
	v_dot2_f32_f16 v151, v124, v75, v151
	v_dot2_f32_f16 v158, v127, v146, 0
	v_dot2_f32_f16 v158, v126, v147, v158
	v_dot2_f32_f16 v158, v125, v148, v158
	v_add_f32_dpp v151, v151, v151 quad_perm:[1,0,3,2] row_mask:0xf bank_mask:0xf bound_ctrl:1
	v_dot2_f32_f16 v158, v124, v149, v158
	ds_read_b128 v[134:137], v114 offset:41856
	v_add_f32_dpp v151, v151, v151 quad_perm:[2,3,0,1] row_mask:0xf bank_mask:0xf bound_ctrl:1
	ds_read_b128 v[138:141], v114 offset:45952
	ds_read_b128 v[142:145], v114 offset:50048
	v_add_f32_dpp v151, v151, v151 row_half_mirror row_mask:0xf bank_mask:0xf bound_ctrl:1
	v_cvt_pkrtz_f16_f32 v152, -v151, -v151
	s_waitcnt lgkmcnt(7)
	v_pk_mul_f16 v153, v152, v68
	v_pk_mul_f16 v154, v152, v69
	ds_read_b128 v[130:133], v167 offset:29568
	v_pk_mul_f16 v155, v152, v70
	v_pk_mul_f16 v156, v152, v71
	s_waitcnt lgkmcnt(6)
	v_pk_fma_f16 v153, v214, v64, v153
	v_pk_fma_f16 v154, v214, v65, v154
	ds_read_b128 v[146:149], v114 offset:54144
	v_pk_fma_f16 v155, v214, v66, v155
	v_pk_fma_f16 v156, v214, v67, v156
	s_waitcnt lgkmcnt(6)
	v_pk_fma_f16 v127, v127, v60, v153
	v_pk_fma_f16 v126, v126, v61, v154
	ds_write2st64_b32 v116, v157, v158 offset0:16 offset1:24
	v_pk_fma_f16 v125, v125, v62, v155
	v_pk_fma_f16 v124, v124, v63, v156
	s_waitcnt lgkmcnt(5)
	v_dot2_f32_f16 v151, v127, v134, 0
	v_dot2_f32_f16 v151, v126, v135, v151
	v_dot2_f32_f16 v151, v125, v136, v151
	v_dot2_f32_f16 v151, v124, v137, v151
	v_dot2_f32_f16 v157, v127, v56, 0
	v_dot2_f32_f16 v157, v126, v57, v157
	v_dot2_f32_f16 v157, v125, v58, v157
	v_add_f32_dpp v151, v151, v151 quad_perm:[1,0,3,2] row_mask:0xf bank_mask:0xf bound_ctrl:1
	v_dot2_f32_f16 v157, v124, v59, v157
	ds_read_b128 v[72:75], v114 offset:41984
	v_add_f32_dpp v151, v151, v151 quad_perm:[2,3,0,1] row_mask:0xf bank_mask:0xf bound_ctrl:1
	ds_read_b128 v[68:71], v114 offset:46080
	ds_read_b128 v[64:67], v114 offset:50176
	v_add_f32_dpp v151, v151, v151 row_half_mirror row_mask:0xf bank_mask:0xf bound_ctrl:1
	v_cvt_pkrtz_f16_f32 v152, -v151, -v151
	s_waitcnt lgkmcnt(7)
	v_pk_mul_f16 v153, v152, v138
	v_pk_mul_f16 v154, v152, v139
	ds_read2st64_b32 v[216:217], v115 offset0:6 offset1:7
	v_pk_mul_f16 v155, v152, v140
	v_pk_mul_f16 v156, v152, v141
	s_waitcnt lgkmcnt(7)
	v_pk_fma_f16 v153, v215, v142, v153
	v_pk_fma_f16 v154, v215, v143, v154
	ds_read_b128 v[60:63], v167 offset:29696
	v_pk_fma_f16 v155, v215, v144, v155
	v_pk_fma_f16 v156, v215, v145, v156
	s_waitcnt lgkmcnt(7)
	v_pk_fma_f16 v127, v127, v130, v153
	v_pk_fma_f16 v126, v126, v131, v154
	ds_read_b128 v[56:59], v114 offset:54272
	v_pk_fma_f16 v125, v125, v132, v155
	v_pk_fma_f16 v124, v124, v133, v156
	s_waitcnt lgkmcnt(5)
	v_dot2_f32_f16 v151, v127, v72, 0
	v_dot2_f32_f16 v151, v126, v73, v151
	v_dot2_f32_f16 v151, v125, v74, v151
	v_dot2_f32_f16 v151, v124, v75, v151
	v_dot2_f32_f16 v158, v127, v146, 0
	v_dot2_f32_f16 v158, v126, v147, v158
	v_dot2_f32_f16 v158, v125, v148, v158
	v_add_f32_dpp v151, v151, v151 quad_perm:[1,0,3,2] row_mask:0xf bank_mask:0xf bound_ctrl:1
	v_dot2_f32_f16 v158, v124, v149, v158
	ds_read_b128 v[134:137], v114 offset:42112
	v_add_f32_dpp v151, v151, v151 quad_perm:[2,3,0,1] row_mask:0xf bank_mask:0xf bound_ctrl:1
	ds_read_b128 v[138:141], v114 offset:46208
	ds_read_b128 v[142:145], v114 offset:50304
	v_add_f32_dpp v151, v151, v151 row_half_mirror row_mask:0xf bank_mask:0xf bound_ctrl:1
	v_cvt_pkrtz_f16_f32 v152, -v151, -v151
	s_waitcnt lgkmcnt(7)
	v_pk_mul_f16 v153, v152, v68
	v_pk_mul_f16 v154, v152, v69
	ds_read_b128 v[130:133], v167 offset:29824
	v_pk_mul_f16 v155, v152, v70
	v_pk_mul_f16 v156, v152, v71
	s_waitcnt lgkmcnt(6)
	v_pk_fma_f16 v153, v216, v64, v153
	v_pk_fma_f16 v154, v216, v65, v154
	ds_read_b128 v[146:149], v114 offset:54400
	v_pk_fma_f16 v155, v216, v66, v155
	v_pk_fma_f16 v156, v216, v67, v156
	s_waitcnt lgkmcnt(6)
	v_pk_fma_f16 v127, v127, v60, v153
	v_pk_fma_f16 v126, v126, v61, v154
	ds_write2st64_b32 v116, v157, v158 offset0:32 offset1:40
	v_pk_fma_f16 v125, v125, v62, v155
	v_pk_fma_f16 v124, v124, v63, v156
	s_waitcnt lgkmcnt(5)
	v_dot2_f32_f16 v151, v127, v134, 0
	v_dot2_f32_f16 v151, v126, v135, v151
	v_dot2_f32_f16 v151, v125, v136, v151
	v_dot2_f32_f16 v151, v124, v137, v151
	v_dot2_f32_f16 v157, v127, v56, 0
	v_dot2_f32_f16 v157, v126, v57, v157
	v_dot2_f32_f16 v157, v125, v58, v157
	v_add_f32_dpp v151, v151, v151 quad_perm:[1,0,3,2] row_mask:0xf bank_mask:0xf bound_ctrl:1
	v_dot2_f32_f16 v157, v124, v59, v157
	ds_read_b128 v[72:75], v114 offset:42240
	v_add_f32_dpp v151, v151, v151 quad_perm:[2,3,0,1] row_mask:0xf bank_mask:0xf bound_ctrl:1
	ds_read_b128 v[68:71], v114 offset:46336
	ds_read_b128 v[64:67], v114 offset:50432
	v_add_f32_dpp v151, v151, v151 row_half_mirror row_mask:0xf bank_mask:0xf bound_ctrl:1
	v_cvt_pkrtz_f16_f32 v152, -v151, -v151
	s_waitcnt lgkmcnt(7)
	v_pk_mul_f16 v153, v152, v138
	v_pk_mul_f16 v154, v152, v139
	ds_read2st64_b32 v[214:215], v115 offset0:8 offset1:9
	v_pk_mul_f16 v155, v152, v140
	v_pk_mul_f16 v156, v152, v141
	s_waitcnt lgkmcnt(7)
	v_pk_fma_f16 v153, v217, v142, v153
	v_pk_fma_f16 v154, v217, v143, v154
	ds_read_b128 v[60:63], v167 offset:29952
	v_pk_fma_f16 v155, v217, v144, v155
	v_pk_fma_f16 v156, v217, v145, v156
	s_waitcnt lgkmcnt(7)
	v_pk_fma_f16 v127, v127, v130, v153
	v_pk_fma_f16 v126, v126, v131, v154
	ds_read_b128 v[56:59], v114 offset:54528
	v_pk_fma_f16 v125, v125, v132, v155
	v_pk_fma_f16 v124, v124, v133, v156
	s_waitcnt lgkmcnt(5)
	v_dot2_f32_f16 v151, v127, v72, 0
	v_dot2_f32_f16 v151, v126, v73, v151
	v_dot2_f32_f16 v151, v125, v74, v151
	v_dot2_f32_f16 v151, v124, v75, v151
	v_dot2_f32_f16 v158, v127, v146, 0
	v_dot2_f32_f16 v158, v126, v147, v158
	v_dot2_f32_f16 v158, v125, v148, v158
	v_add_f32_dpp v151, v151, v151 quad_perm:[1,0,3,2] row_mask:0xf bank_mask:0xf bound_ctrl:1
	v_dot2_f32_f16 v158, v124, v149, v158
	ds_read_b128 v[134:137], v114 offset:42368
	v_add_f32_dpp v151, v151, v151 quad_perm:[2,3,0,1] row_mask:0xf bank_mask:0xf bound_ctrl:1
	ds_read_b128 v[138:141], v114 offset:46464
	ds_read_b128 v[142:145], v114 offset:50560
	v_add_f32_dpp v151, v151, v151 row_half_mirror row_mask:0xf bank_mask:0xf bound_ctrl:1
	v_cvt_pkrtz_f16_f32 v152, -v151, -v151
	s_waitcnt lgkmcnt(7)
	v_pk_mul_f16 v153, v152, v68
	v_pk_mul_f16 v154, v152, v69
	ds_read_b128 v[130:133], v167 offset:30080
	v_pk_mul_f16 v155, v152, v70
	v_pk_mul_f16 v156, v152, v71
	s_waitcnt lgkmcnt(6)
	v_pk_fma_f16 v153, v214, v64, v153
	v_pk_fma_f16 v154, v214, v65, v154
	ds_read_b128 v[146:149], v114 offset:54656
	v_pk_fma_f16 v155, v214, v66, v155
	v_pk_fma_f16 v156, v214, v67, v156
	s_waitcnt lgkmcnt(6)
	v_pk_fma_f16 v127, v127, v60, v153
	v_pk_fma_f16 v126, v126, v61, v154
	ds_write2st64_b32 v116, v157, v158 offset0:48 offset1:56
	v_pk_fma_f16 v125, v125, v62, v155
	v_pk_fma_f16 v124, v124, v63, v156
	s_waitcnt lgkmcnt(5)
	v_dot2_f32_f16 v151, v127, v134, 0
	v_dot2_f32_f16 v151, v126, v135, v151
	v_dot2_f32_f16 v151, v125, v136, v151
	v_dot2_f32_f16 v151, v124, v137, v151
	v_dot2_f32_f16 v157, v127, v56, 0
	v_dot2_f32_f16 v157, v126, v57, v157
	v_dot2_f32_f16 v157, v125, v58, v157
	v_add_f32_dpp v151, v151, v151 quad_perm:[1,0,3,2] row_mask:0xf bank_mask:0xf bound_ctrl:1
	v_dot2_f32_f16 v157, v124, v59, v157
	ds_read_b128 v[72:75], v114 offset:42496
	v_add_f32_dpp v151, v151, v151 quad_perm:[2,3,0,1] row_mask:0xf bank_mask:0xf bound_ctrl:1
	ds_read_b128 v[68:71], v114 offset:46592
	ds_read_b128 v[64:67], v114 offset:50688
	v_add_f32_dpp v151, v151, v151 row_half_mirror row_mask:0xf bank_mask:0xf bound_ctrl:1
	v_cvt_pkrtz_f16_f32 v152, -v151, -v151
	s_waitcnt lgkmcnt(7)
	v_pk_mul_f16 v153, v152, v138
	v_pk_mul_f16 v154, v152, v139
	ds_read2st64_b32 v[216:217], v115 offset0:10 offset1:11
	v_pk_mul_f16 v155, v152, v140
	v_pk_mul_f16 v156, v152, v141
	s_waitcnt lgkmcnt(7)
	v_pk_fma_f16 v153, v215, v142, v153
	v_pk_fma_f16 v154, v215, v143, v154
	ds_read_b128 v[60:63], v167 offset:30208
	v_pk_fma_f16 v155, v215, v144, v155
	v_pk_fma_f16 v156, v215, v145, v156
	s_waitcnt lgkmcnt(7)
	v_pk_fma_f16 v127, v127, v130, v153
	v_pk_fma_f16 v126, v126, v131, v154
	ds_read_b128 v[56:59], v114 offset:54784
	v_pk_fma_f16 v125, v125, v132, v155
	v_pk_fma_f16 v124, v124, v133, v156
	s_waitcnt lgkmcnt(5)
	v_dot2_f32_f16 v151, v127, v72, 0
	v_dot2_f32_f16 v151, v126, v73, v151
	v_dot2_f32_f16 v151, v125, v74, v151
	v_dot2_f32_f16 v151, v124, v75, v151
	v_dot2_f32_f16 v158, v127, v146, 0
	v_dot2_f32_f16 v158, v126, v147, v158
	v_dot2_f32_f16 v158, v125, v148, v158
	v_add_f32_dpp v151, v151, v151 quad_perm:[1,0,3,2] row_mask:0xf bank_mask:0xf bound_ctrl:1
	v_dot2_f32_f16 v158, v124, v149, v158
	ds_read_b128 v[134:137], v114 offset:42624
	v_add_f32_dpp v151, v151, v151 quad_perm:[2,3,0,1] row_mask:0xf bank_mask:0xf bound_ctrl:1
	ds_read_b128 v[138:141], v114 offset:46720
	ds_read_b128 v[142:145], v114 offset:50816
	v_add_f32_dpp v151, v151, v151 row_half_mirror row_mask:0xf bank_mask:0xf bound_ctrl:1
	v_cvt_pkrtz_f16_f32 v152, -v151, -v151
	s_waitcnt lgkmcnt(7)
	v_pk_mul_f16 v153, v152, v68
	v_pk_mul_f16 v154, v152, v69
	ds_read_b128 v[130:133], v167 offset:30336
	v_pk_mul_f16 v155, v152, v70
	v_pk_mul_f16 v156, v152, v71
	s_waitcnt lgkmcnt(6)
	v_pk_fma_f16 v153, v216, v64, v153
	v_pk_fma_f16 v154, v216, v65, v154
	ds_read_b128 v[146:149], v114 offset:54912
	v_pk_fma_f16 v155, v216, v66, v155
	v_pk_fma_f16 v156, v216, v67, v156
	s_waitcnt lgkmcnt(6)
	v_pk_fma_f16 v127, v127, v60, v153
	v_pk_fma_f16 v126, v126, v61, v154
	ds_write2st64_b32 v116, v157, v158 offset0:64 offset1:72
	v_pk_fma_f16 v125, v125, v62, v155
	v_pk_fma_f16 v124, v124, v63, v156
	s_waitcnt lgkmcnt(5)
	v_dot2_f32_f16 v151, v127, v134, 0
	v_dot2_f32_f16 v151, v126, v135, v151
	v_dot2_f32_f16 v151, v125, v136, v151
	v_dot2_f32_f16 v151, v124, v137, v151
	v_dot2_f32_f16 v157, v127, v56, 0
	v_dot2_f32_f16 v157, v126, v57, v157
	v_dot2_f32_f16 v157, v125, v58, v157
	v_add_f32_dpp v151, v151, v151 quad_perm:[1,0,3,2] row_mask:0xf bank_mask:0xf bound_ctrl:1
	v_dot2_f32_f16 v157, v124, v59, v157
	ds_read_b128 v[72:75], v114 offset:42752
	v_add_f32_dpp v151, v151, v151 quad_perm:[2,3,0,1] row_mask:0xf bank_mask:0xf bound_ctrl:1
	ds_read_b128 v[68:71], v114 offset:46848
	ds_read_b128 v[64:67], v114 offset:50944
	v_add_f32_dpp v151, v151, v151 row_half_mirror row_mask:0xf bank_mask:0xf bound_ctrl:1
	v_cvt_pkrtz_f16_f32 v152, -v151, -v151
	s_waitcnt lgkmcnt(7)
	v_pk_mul_f16 v153, v152, v138
	v_pk_mul_f16 v154, v152, v139
	ds_read2st64_b32 v[214:215], v115 offset0:12 offset1:13
	v_pk_mul_f16 v155, v152, v140
	v_pk_mul_f16 v156, v152, v141
	s_waitcnt lgkmcnt(7)
	v_pk_fma_f16 v153, v217, v142, v153
	v_pk_fma_f16 v154, v217, v143, v154
	ds_read_b128 v[60:63], v167 offset:30464
	v_pk_fma_f16 v155, v217, v144, v155
	v_pk_fma_f16 v156, v217, v145, v156
	s_waitcnt lgkmcnt(7)
	v_pk_fma_f16 v127, v127, v130, v153
	v_pk_fma_f16 v126, v126, v131, v154
	ds_read_b128 v[56:59], v114 offset:55040
	v_pk_fma_f16 v125, v125, v132, v155
	v_pk_fma_f16 v124, v124, v133, v156
	s_waitcnt lgkmcnt(5)
	v_dot2_f32_f16 v151, v127, v72, 0
	v_dot2_f32_f16 v151, v126, v73, v151
	v_dot2_f32_f16 v151, v125, v74, v151
	v_dot2_f32_f16 v151, v124, v75, v151
	v_dot2_f32_f16 v158, v127, v146, 0
	v_dot2_f32_f16 v158, v126, v147, v158
	v_dot2_f32_f16 v158, v125, v148, v158
	v_add_f32_dpp v151, v151, v151 quad_perm:[1,0,3,2] row_mask:0xf bank_mask:0xf bound_ctrl:1
	v_dot2_f32_f16 v158, v124, v149, v158
	ds_read_b128 v[134:137], v114 offset:42880
	v_add_f32_dpp v151, v151, v151 quad_perm:[2,3,0,1] row_mask:0xf bank_mask:0xf bound_ctrl:1
	ds_read_b128 v[138:141], v114 offset:46976
	ds_read_b128 v[142:145], v114 offset:51072
	v_add_f32_dpp v151, v151, v151 row_half_mirror row_mask:0xf bank_mask:0xf bound_ctrl:1
	v_cvt_pkrtz_f16_f32 v152, -v151, -v151
	s_waitcnt lgkmcnt(7)
	v_pk_mul_f16 v153, v152, v68
	v_pk_mul_f16 v154, v152, v69
	ds_read_b128 v[130:133], v167 offset:30592
	v_pk_mul_f16 v155, v152, v70
	v_pk_mul_f16 v156, v152, v71
	s_waitcnt lgkmcnt(6)
	v_pk_fma_f16 v153, v214, v64, v153
	v_pk_fma_f16 v154, v214, v65, v154
	ds_read_b128 v[146:149], v114 offset:55168
	v_pk_fma_f16 v155, v214, v66, v155
	v_pk_fma_f16 v156, v214, v67, v156
	s_waitcnt lgkmcnt(6)
	v_pk_fma_f16 v127, v127, v60, v153
	v_pk_fma_f16 v126, v126, v61, v154
	ds_write2st64_b32 v116, v157, v158 offset0:80 offset1:88
	v_pk_fma_f16 v125, v125, v62, v155
	v_pk_fma_f16 v124, v124, v63, v156
	s_waitcnt lgkmcnt(5)
	v_dot2_f32_f16 v151, v127, v134, 0
	v_dot2_f32_f16 v151, v126, v135, v151
	v_dot2_f32_f16 v151, v125, v136, v151
	v_dot2_f32_f16 v151, v124, v137, v151
	v_dot2_f32_f16 v157, v127, v56, 0
	v_dot2_f32_f16 v157, v126, v57, v157
	v_dot2_f32_f16 v157, v125, v58, v157
	v_add_f32_dpp v151, v151, v151 quad_perm:[1,0,3,2] row_mask:0xf bank_mask:0xf bound_ctrl:1
	v_dot2_f32_f16 v157, v124, v59, v157
	ds_read_b128 v[72:75], v114 offset:43008
	v_add_f32_dpp v151, v151, v151 quad_perm:[2,3,0,1] row_mask:0xf bank_mask:0xf bound_ctrl:1
	ds_read_b128 v[68:71], v114 offset:47104
	ds_read_b128 v[64:67], v114 offset:51200
	v_add_f32_dpp v151, v151, v151 row_half_mirror row_mask:0xf bank_mask:0xf bound_ctrl:1
	v_cvt_pkrtz_f16_f32 v152, -v151, -v151
	s_waitcnt lgkmcnt(7)
	v_pk_mul_f16 v153, v152, v138
	v_pk_mul_f16 v154, v152, v139
	ds_read2st64_b32 v[216:217], v115 offset0:14 offset1:15
	v_pk_mul_f16 v155, v152, v140
	v_pk_mul_f16 v156, v152, v141
	s_waitcnt lgkmcnt(7)
	v_pk_fma_f16 v153, v215, v142, v153
	v_pk_fma_f16 v154, v215, v143, v154
	ds_read_b128 v[60:63], v167 offset:30720
	v_pk_fma_f16 v155, v215, v144, v155
	v_pk_fma_f16 v156, v215, v145, v156
	s_waitcnt lgkmcnt(7)
	v_pk_fma_f16 v127, v127, v130, v153
	v_pk_fma_f16 v126, v126, v131, v154
	ds_read_b128 v[56:59], v114 offset:55296
	v_pk_fma_f16 v125, v125, v132, v155
	v_pk_fma_f16 v124, v124, v133, v156
	s_waitcnt lgkmcnt(5)
	v_dot2_f32_f16 v151, v127, v72, 0
	v_dot2_f32_f16 v151, v126, v73, v151
	v_dot2_f32_f16 v151, v125, v74, v151
	v_dot2_f32_f16 v151, v124, v75, v151
	v_dot2_f32_f16 v158, v127, v146, 0
	v_dot2_f32_f16 v158, v126, v147, v158
	v_dot2_f32_f16 v158, v125, v148, v158
	v_add_f32_dpp v151, v151, v151 quad_perm:[1,0,3,2] row_mask:0xf bank_mask:0xf bound_ctrl:1
	v_dot2_f32_f16 v158, v124, v149, v158
	ds_read_b128 v[134:137], v114 offset:43136
	v_add_f32_dpp v151, v151, v151 quad_perm:[2,3,0,1] row_mask:0xf bank_mask:0xf bound_ctrl:1
	ds_read_b128 v[138:141], v114 offset:47232
	ds_read_b128 v[142:145], v114 offset:51328
	v_add_f32_dpp v151, v151, v151 row_half_mirror row_mask:0xf bank_mask:0xf bound_ctrl:1
	v_cvt_pkrtz_f16_f32 v152, -v151, -v151
	s_waitcnt lgkmcnt(7)
	v_pk_mul_f16 v153, v152, v68
	v_pk_mul_f16 v154, v152, v69
	ds_read_b128 v[130:133], v167 offset:30848
	v_pk_mul_f16 v155, v152, v70
	v_pk_mul_f16 v156, v152, v71
	s_waitcnt lgkmcnt(6)
	v_pk_fma_f16 v153, v216, v64, v153
	v_pk_fma_f16 v154, v216, v65, v154
	ds_read_b128 v[146:149], v114 offset:55424
	v_pk_fma_f16 v155, v216, v66, v155
	v_pk_fma_f16 v156, v216, v67, v156
	s_waitcnt lgkmcnt(6)
	v_pk_fma_f16 v127, v127, v60, v153
	v_pk_fma_f16 v126, v126, v61, v154
	ds_write2st64_b32 v116, v157, v158 offset0:96 offset1:104
	v_pk_fma_f16 v125, v125, v62, v155
	v_pk_fma_f16 v124, v124, v63, v156
	s_waitcnt lgkmcnt(5)
	v_dot2_f32_f16 v151, v127, v134, 0
	v_dot2_f32_f16 v151, v126, v135, v151
	v_dot2_f32_f16 v151, v125, v136, v151
	v_dot2_f32_f16 v151, v124, v137, v151
	v_dot2_f32_f16 v157, v127, v56, 0
	v_dot2_f32_f16 v157, v126, v57, v157
	v_dot2_f32_f16 v157, v125, v58, v157
	v_add_f32_dpp v151, v151, v151 quad_perm:[1,0,3,2] row_mask:0xf bank_mask:0xf bound_ctrl:1
	v_dot2_f32_f16 v157, v124, v59, v157
	s_nop 0
	v_add_f32_dpp v151, v151, v151 quad_perm:[2,3,0,1] row_mask:0xf bank_mask:0xf bound_ctrl:1
	s_nop 1
	v_add_f32_dpp v151, v151, v151 row_half_mirror row_mask:0xf bank_mask:0xf bound_ctrl:1
	v_cvt_pkrtz_f16_f32 v152, -v151, -v151
	s_waitcnt lgkmcnt(4)
	v_pk_mul_f16 v153, v152, v138
	v_pk_mul_f16 v154, v152, v139
	v_pk_mul_f16 v155, v152, v140
	v_pk_mul_f16 v156, v152, v141
	s_waitcnt lgkmcnt(3)
	v_pk_fma_f16 v153, v217, v142, v153
	v_pk_fma_f16 v154, v217, v143, v154
	v_pk_fma_f16 v155, v217, v144, v155
	v_pk_fma_f16 v156, v217, v145, v156
	s_waitcnt lgkmcnt(2)
	v_pk_fma_f16 v127, v127, v130, v153
	v_pk_fma_f16 v126, v126, v131, v154
	v_pk_fma_f16 v125, v125, v132, v155
	v_pk_fma_f16 v124, v124, v133, v156
	s_waitcnt lgkmcnt(1)
	v_dot2_f32_f16 v158, v127, v146, 0
	v_dot2_f32_f16 v158, v126, v147, v158
	v_dot2_f32_f16 v158, v125, v148, v158
	v_dot2_f32_f16 v158, v124, v149, v158
	s_nop 2
	ds_write2st64_b32 v116, v157, v158 offset0:112 offset1:120
	s_xor_b32 s100, s100, 0xe100
	s_cmpk_lg_i32 s30, 0x80
	s_cbranch_scc0 .LBB0_1250
	s_mov_b32 s4, s30
	s_and_saveexec_b64 s[18:19], s[10:11]
	s_cbranch_execnz .LBB0_1229
	s_branch .LBB0_1230
